# grid barrier polling loops sleep 6 instead of 1 between flag polls
# speedup vs baseline: 1.0086x; 1.0037x over previous
; __global__ void __launch_bounds__(512) mega_fwd(Params p) {
;     ...
;   grid.sync();
.Lgsync_spin_1:
	global_atomic_add v2, v0, v3, s[8:9] sc0
	s_waitcnt vmcnt(0)
	v_readfirstlane_b32 s0, v2
	s_nop 0
	s_cmp_ge_u32 s0, s11
	s_cbranch_scc1 .Lgsync_done_1
	s_add_i32 s12, s12, -1
	s_cmp_eq_u32 s12, 0
	s_cbranch_scc1 .Lgsync_done_1
	s_sleep 6
	s_branch .Lgsync_spin_1

; __global__ void __launch_bounds__(512) mega_fwd(Params p) {
;     ...
;   grid.sync();
.Lgsync_spin_2:
	global_atomic_add v2, v0, v3, s[10:11] sc0
	s_waitcnt vmcnt(0)
	v_readfirstlane_b32 s0, v2
	s_nop 0
	s_cmp_ge_u32 s0, s13
	s_cbranch_scc1 .Lgsync_done_2
	s_add_i32 s44, s44, -1
	s_cmp_eq_u32 s44, 0
	s_cbranch_scc1 .Lgsync_done_2
	s_sleep 6
	s_branch .Lgsync_spin_2

; __global__ void __launch_bounds__(512) mega_fwd(Params p) {
;     ...
;   grid.sync();
.Lgsync_spin_3:
	global_atomic_add v2, v0, v3, s[10:11] sc0
	s_waitcnt vmcnt(0)
	v_readfirstlane_b32 s0, v2
	s_nop 0
	s_cmp_ge_u32 s0, s13
	s_cbranch_scc1 .Lgsync_done_3
	s_add_i32 s16, s16, -1
	s_cmp_eq_u32 s16, 0
	s_cbranch_scc1 .Lgsync_done_3
	s_sleep 6
	s_branch .Lgsync_spin_3

; __global__ void __launch_bounds__(512) mega_fwd(Params p) {
;     ...
;   grid.sync();
.Lgsync_spin_4:
	global_atomic_add v2, v0, v3, s[10:11] sc0
	s_waitcnt vmcnt(0)
	v_readfirstlane_b32 s0, v2
	s_nop 0
	s_cmp_ge_u32 s0, s13
	s_cbranch_scc1 .Lgsync_done_4
	s_add_i32 s14, s14, -1
	s_cmp_eq_u32 s14, 0
	s_cbranch_scc1 .Lgsync_done_4
	s_sleep 6
	s_branch .Lgsync_spin_4

; __global__ void __launch_bounds__(512) mega_fwd(Params p) {
;     ...
;   grid.sync();
.Lgsync_spin_8:
	global_atomic_add v2, v0, v3, s[8:9] sc0
	s_waitcnt vmcnt(0)
	v_readfirstlane_b32 s0, v2
	s_nop 0
	s_cmp_ge_u32 s0, s11
	s_cbranch_scc1 .Lgsync_done_8
	s_add_i32 s4, s4, -1
	s_cmp_eq_u32 s4, 0
	s_cbranch_scc1 .Lgsync_done_8
	s_sleep 6
	s_branch .Lgsync_spin_8
